# k16 + guf_cwpre: gate/up epilogue conv-weight loads prefetched before the k-loop, epilogue no longer drains vmcnt(0)
# speedup vs baseline: 1.0286x; 1.0021x over previous
; template <class Epi>
; __device__ __forceinline__ void gemm_phase(LAS unsigned char* lds, const Gemm g, const StaticOrder& S, const Epi& E, int wave) {
;     ...
;         for (int a = 0; a < 2; ++a)
; #pragma unroll
;             for (int b = 0; b < 2; ++b)
; #pragma unroll
;                 for (int m = 0; m < 4; ++m)
; #pragma unroll
;                     for (int n = 0; n < 2; ++n) acc[a][b][m][n] = (f32x4){0.f, 0.f, 0.f, 0.f};
;     __device__ __forceinline__ void operator()(f32x4 (&acc)[2][2][4][2], const pg8::Unit& u, int wr, int wc, int, int) const {
;     ...
;         { const int p0 = ln_ >> 5, col = ln_ & 31, fb = u.pn * 128 + wc * 32;
;           const float a_ = cw[p0 * DFF + fb + col]; const float b_ = (p0 == 0) ? cw[2 * DFF + fb + col] : cb[fb + col];
;           lwv[p0 * 32 + col] = a_; lwv[(p0 + 2) * 32 + col] = b_; }
.LBB0_809:
	s_ashr_i32 s21, s20, 31
	v_cmp_lt_i64_e32 vcc, s[22:23], v[140:141]
	s_lshl_b64 s[22:23], s[20:21], 19
	s_add_u32 s22, s66, s22
	s_addc_u32 s23, s67, s23
	s_and_b64 s[24:25], vcc, exec
	s_cselect_b32 s21, s23, s5
	s_cselect_b32 s27, s22, s4
	s_ashr_i32 s19, s18, 31
	s_lshl_b64 s[24:25], s[18:19], 19
	s_add_u32 s24, s34, s24
	s_addc_u32 s25, s35, s25
	s_and_b64 s[28:29], vcc, exec
	s_cselect_b32 s19, s25, s7
	s_cselect_b32 s30, s24, s6
	s_add_u32 s4, s4, 0x40080
	s_addc_u32 s5, s5, 0
	s_add_u32 s31, s6, 0x100
	v_mov_b32_e32 v24, 0
	s_addc_u32 s54, s7, 0
	s_mov_b32 s55, -2
	v_readlane_b32 s98, v253, 0
	v_readlane_b32 s99, v253, 1
	v_readlane_b32 s100, v253, 2
	v_readlane_b32 s101, v253, 3
	v_mbcnt_lo_u32_b32 v146, -1, 0
	v_mbcnt_hi_u32_b32 v146, -1, v146
	v_mov_b32_e32 v147, s46
	v_lshl_or_b32 v147, s3, 7, v147
	v_lshrrev_b32_e32 v144, 5, v146
	v_and_b32_e32 v148, 31, v146
	v_mul_u32_u24_e32 v144, 0xb00, v144
	v_add_u32_e32 v144, v147, v144
	v_or_b32_e32 v144, v144, v148
	v_mov_b32_e32 v145, 0
	v_lshl_add_u64 v[144:145], v[144:145], 2, s[98:99]
	global_load_dword v252, v[144:145], off
	v_or_b32_e32 v144, v147, v148
	v_add_u32_e32 v145, 0x1600, v147
	v_add_u32_e32 v145, v145, v146
	v_cmp_gt_u32_e32 vcc, 32, v146
	v_mov_b32_e32 v148, s99
	v_mov_b32_e32 v149, s101
	v_cndmask_b32_e32 v144, v144, v145, vcc
	v_cndmask_b32_e32 v149, v149, v148, vcc
	v_mov_b32_e32 v145, s100
	v_mov_b32_e32 v148, s98
	v_cndmask_b32_e32 v148, v145, v148, vcc
	v_mov_b32_e32 v145, 0
	v_lshl_add_u64 v[144:145], v[144:145], 2, v[148:149]
	global_load_dword v255, v[144:145], off
	v_mov_b32_e32 v25, v24
	v_mov_b32_e32 v26, v24
	v_mov_b32_e32 v27, v24
	v_mov_b32_e32 v0, v24
	v_mov_b32_e32 v1, v24
	v_mov_b32_e32 v2, v24
	v_mov_b32_e32 v3, v24
	v_mov_b32_e32 v32, v24
	v_mov_b32_e32 v33, v24
	v_mov_b32_e32 v34, v24
	v_mov_b32_e32 v35, v24
	v_mov_b32_e32 v4, v24
	v_mov_b32_e32 v5, v24
	v_mov_b32_e32 v6, v24
	v_mov_b32_e32 v7, v24
	v_mov_b32_e32 v28, v24
	v_mov_b32_e32 v29, v24
	v_mov_b32_e32 v30, v24
	v_mov_b32_e32 v31, v24
	v_mov_b32_e32 v8, v24
	v_mov_b32_e32 v9, v24
	v_mov_b32_e32 v10, v24
	v_mov_b32_e32 v11, v24
	v_mov_b32_e32 v36, v24
	v_mov_b32_e32 v37, v24
	v_mov_b32_e32 v38, v24
	v_mov_b32_e32 v39, v24
	v_mov_b32_e32 v12, v24
	v_mov_b32_e32 v13, v24
	v_mov_b32_e32 v14, v24
	v_mov_b32_e32 v15, v24
	v_mov_b32_e32 v48, v24
	v_mov_b32_e32 v49, v24
	v_mov_b32_e32 v50, v24
	v_mov_b32_e32 v51, v24
	v_mov_b32_e32 v56, v24
	v_mov_b32_e32 v57, v24
	v_mov_b32_e32 v58, v24
	v_mov_b32_e32 v59, v24
	v_mov_b32_e32 v44, v24
	v_mov_b32_e32 v45, v24
	v_mov_b32_e32 v46, v24
	v_mov_b32_e32 v47, v24
	v_mov_b32_e32 v20, v24
	v_mov_b32_e32 v21, v24
	v_mov_b32_e32 v22, v24
	v_mov_b32_e32 v23, v24
	v_mov_b32_e32 v40, v24
	v_mov_b32_e32 v41, v24
	v_mov_b32_e32 v42, v24
	v_mov_b32_e32 v43, v24
	v_mov_b32_e32 v16, v24
	v_mov_b32_e32 v17, v24
	v_mov_b32_e32 v18, v24
	v_mov_b32_e32 v19, v24
	v_mov_b32_e32 v52, v24
	v_mov_b32_e32 v53, v24
	v_mov_b32_e32 v54, v24
	v_mov_b32_e32 v55, v24
	v_mov_b32_e32 v60, v24
	v_mov_b32_e32 v61, v24
	v_mov_b32_e32 v62, v24
	v_mov_b32_e32 v63, v24
	v_mov_b32_e32 v88, v24
	v_mov_b32_e32 v89, v24
	v_mov_b32_e32 v90, v24
	v_mov_b32_e32 v91, v24
	v_mov_b32_e32 v64, v24
	v_mov_b32_e32 v65, v24
	v_mov_b32_e32 v66, v24
	v_mov_b32_e32 v67, v24
	v_mov_b32_e32 v96, v24
	v_mov_b32_e32 v97, v24
	v_mov_b32_e32 v98, v24
	v_mov_b32_e32 v99, v24
	v_mov_b32_e32 v68, v24
	v_mov_b32_e32 v69, v24
	v_mov_b32_e32 v70, v24
	v_mov_b32_e32 v71, v24
	v_mov_b32_e32 v92, v24
	v_mov_b32_e32 v93, v24
	v_mov_b32_e32 v94, v24
	v_mov_b32_e32 v95, v24
	v_mov_b32_e32 v72, v24
	v_mov_b32_e32 v73, v24
	v_mov_b32_e32 v74, v24
	v_mov_b32_e32 v75, v24
	v_mov_b32_e32 v100, v24
	v_mov_b32_e32 v101, v24
	v_mov_b32_e32 v102, v24
	v_mov_b32_e32 v103, v24
	v_mov_b32_e32 v76, v24
	v_mov_b32_e32 v77, v24
	v_mov_b32_e32 v78, v24
	v_mov_b32_e32 v79, v24
	v_mov_b32_e32 v112, v24
	v_mov_b32_e32 v113, v24
	v_mov_b32_e32 v114, v24
	v_mov_b32_e32 v115, v24
	v_mov_b32_e32 v120, v24
	v_mov_b32_e32 v121, v24
	v_mov_b32_e32 v122, v24
	v_mov_b32_e32 v123, v24
	v_mov_b32_e32 v108, v24
	v_mov_b32_e32 v109, v24
	v_mov_b32_e32 v110, v24
	v_mov_b32_e32 v111, v24
	v_mov_b32_e32 v84, v24
	v_mov_b32_e32 v85, v24
	v_mov_b32_e32 v86, v24
	v_mov_b32_e32 v87, v24
	v_mov_b32_e32 v104, v24
	v_mov_b32_e32 v105, v24
	v_mov_b32_e32 v106, v24
	v_mov_b32_e32 v107, v24
	v_mov_b32_e32 v80, v24
	v_mov_b32_e32 v81, v24
	v_mov_b32_e32 v82, v24
	v_mov_b32_e32 v83, v24
	v_mov_b32_e32 v116, v24
	v_mov_b32_e32 v117, v24
	v_mov_b32_e32 v118, v24
	v_mov_b32_e32 v119, v24
	v_mov_b32_e32 v124, v24
	v_mov_b32_e32 v125, v24
	v_mov_b32_e32 v126, v24
	v_mov_b32_e32 v127, v24
; #define PG8_STAGE(bufoff, gbase, voff) do { _Pragma("unroll") for (int _i = 0; _i < 2; ++_i) \
;         __builtin_amdgcn_global_load_lds((const unsigned*)((const char*)(gbase) + (voff)[_i]), (LAS unsigned*)(lds + (bufoff) + ldsw + _i * 8192), 16, 0, 0); } while (0)
; #define PG8_LDA(dst, b, h) do { _Pragma("unroll") for (int m = 0; m < 4; ++m) _Pragma("unroll") for (int k = 0; k < 2; ++k) dst[m][k] = *(const LAS bf16x8*)(lds + PG8_SA(b, h) + aoff + m * 2048 + k * 1024); } while (0)
; #define PG8_LDB(dst, b, h) do { _Pragma("unroll") for (int n = 0; n < 2; ++n) _Pragma("unroll") for (int k = 0; k < 2; ++k) dst[n][k] = *(const LAS bf16x8*)(lds + PG8_SB(b, h) + boff + n * 2048 + k * 1024); } while (0)
; #define PG8_MMA(ai, bj, At, Bt) do { __builtin_amdgcn_s_setprio(1); _Pragma("unroll") for (int m = 0; m < 4; ++m) _Pragma("unroll") for (int n = 0; n < 2; ++n) _Pragma("unroll") for (int k = 0; k < 2; ++k) \
;         acc[ai][bj][m][n] = __builtin_amdgcn_mfma_f32_16x16x32_bf16(Bt[n][k], At[m][k], acc[ai][bj][m][n], 0, 0, 0); __builtin_amdgcn_s_setprio(0); } while (0)
; #define PG8_WAIT_V(n) asm volatile("s_waitcnt vmcnt(" #n ")" ::: "memory")
; #define PG8_WAIT_L(n) asm volatile("s_waitcnt lgkmcnt(" #n ")" ::: "memory")
; #define PG8_BAR __builtin_amdgcn_s_barrier()
; #define PG8_SCHED __builtin_amdgcn_sched_barrier(0)
; template <class Epi>
; __device__ __forceinline__ void gemm_phase(LAS unsigned char* lds, const Gemm g, const StaticOrder& S, const Epi& E, int wave) {
;     ...
;             PG8_LDB(B0, 0, 0); PG8_SCHED; PG8_LDA(At, 0, 0); PG8_STAGE(PG8_SA(1, 1), a1 + hstep, voffA);
;             PG8_WAIT_L(8); PG8_BAR; PG8_WAIT_L(0); PG8_MMA(0, 0, At, B0); PG8_BAR; PG8_SCHED;
;             PG8_LDB(B1, 0, 1); PG8_STAGE(PG8_SB(0, 0), b2, voffB);
;             PG8_BAR; PG8_WAIT_L(0); PG8_MMA(0, 1, At, B1); PG8_BAR;
;             PG8_LDA(At, 0, 1); PG8_STAGE(PG8_SA(0, 0), a2, voffA);
;             PG8_BAR; PG8_WAIT_L(0); PG8_MMA(1, 0, At, B0); PG8_BAR; PG8_SCHED;
;             PG8_STAGE(PG8_SB(0, 1), b2 + hstep, voffB);
;             PG8_WAIT_V(6); PG8_BAR; PG8_MMA(1, 1, At, B1); PG8_BAR;
.LBB0_810:
	ds_read_b128 v[144:147], v189
	ds_read_b128 v[148:151], v189 offset:1024
	ds_read_b128 v[152:155], v189 offset:2048
	ds_read_b128 v[156:159], v189 offset:3072
	s_add_u32 s6, s4, 0xfffc0080
	s_addc_u32 s7, s5, -1
	s_cmp_eq_u32 s55, 12
	s_cselect_b32 s29, s21, s7
	s_cselect_b32 s28, s27, s6
	s_cselect_b32 s7, s19, s54
	s_cselect_b32 s6, s30, s31
	v_lshl_add_u64 v[198:199], s[4:5], 0, v[136:137]
	s_add_i32 m0, s39, 0xc000
	ds_read_b128 v[160:163], v190
	ds_read_b128 v[164:167], v190 offset:1024
	ds_read_b128 v[168:171], v190 offset:2048
	ds_read_b128 v[172:175], v190 offset:3072
	ds_read_b128 v[176:179], v190 offset:4096
	ds_read_b128 v[180:183], v190 offset:5120
	ds_read_b128 v[184:187], v190 offset:6144
	ds_read_b128 v[194:197], v190 offset:7168
	global_load_lds_dwordx4 v[198:199], off
	v_lshl_add_u64 v[198:199], s[4:5], 0, v[138:139]
	s_add_i32 m0, s39, 0xe000
	s_nop 0
	global_load_lds_dwordx4 v[198:199], off
	s_waitcnt lgkmcnt(8)
	s_barrier
	s_waitcnt lgkmcnt(0)
	s_setprio 1
	s_waitcnt lgkmcnt(0)
	v_mfma_f32_16x16x32_bf16 v[124:127], v[144:147], v[160:163], v[124:127]
	v_mfma_f32_16x16x32_bf16 v[116:119], v[152:155], v[160:163], v[116:119]
	v_mfma_f32_16x16x32_bf16 v[80:83], v[144:147], v[168:171], v[80:83]
	v_mfma_f32_16x16x32_bf16 v[104:107], v[152:155], v[168:171], v[104:107]
	v_mfma_f32_16x16x32_bf16 v[84:87], v[144:147], v[176:179], v[84:87]
	v_mfma_f32_16x16x32_bf16 v[108:111], v[152:155], v[176:179], v[108:111]
	v_mfma_f32_16x16x32_bf16 v[120:123], v[144:147], v[184:187], v[120:123]
	v_mfma_f32_16x16x32_bf16 v[112:115], v[152:155], v[184:187], v[112:115]
	v_mfma_f32_16x16x32_bf16 v[124:127], v[148:151], v[164:167], v[124:127]
	v_mfma_f32_16x16x32_bf16 v[116:119], v[156:159], v[164:167], v[116:119]
	v_mfma_f32_16x16x32_bf16 v[80:83], v[148:151], v[172:175], v[80:83]
	v_mfma_f32_16x16x32_bf16 v[104:107], v[156:159], v[172:175], v[104:107]
	v_mfma_f32_16x16x32_bf16 v[84:87], v[148:151], v[180:183], v[84:87]
	v_mfma_f32_16x16x32_bf16 v[108:111], v[156:159], v[180:183], v[108:111]
	v_mfma_f32_16x16x32_bf16 v[120:123], v[148:151], v[194:197], v[120:123]
	v_mfma_f32_16x16x32_bf16 v[112:115], v[156:159], v[194:197], v[112:115]
	s_setprio 0
	s_barrier
	s_add_i32 s56, s50, s36
	v_lshl_add_u64 v[214:215], s[6:7], 0, v[132:133]
	s_mov_b32 m0, s56
	ds_read_b128 v[198:201], v191
	ds_read_b128 v[202:205], v191 offset:1024
	ds_read_b128 v[206:209], v191 offset:2048
	ds_read_b128 v[210:213], v191 offset:3072
	global_load_lds_dwordx4 v[214:215], off
	v_lshl_add_u64 v[216:217], s[6:7], 0, v[128:129]
	s_add_i32 m0, s56, 0x2000
	s_nop 0
	global_load_lds_dwordx4 v[216:217], off
	s_barrier
	s_waitcnt lgkmcnt(0)
	s_setprio 1
	s_waitcnt lgkmcnt(0)
	v_mfma_f32_16x16x32_bf16 v[76:79], v[198:201], v[160:163], v[76:79]
	v_mfma_f32_16x16x32_bf16 v[100:103], v[206:209], v[160:163], v[100:103]
	v_mfma_f32_16x16x32_bf16 v[72:75], v[198:201], v[168:171], v[72:75]
	v_mfma_f32_16x16x32_bf16 v[92:95], v[206:209], v[168:171], v[92:95]
	v_mfma_f32_16x16x32_bf16 v[68:71], v[198:201], v[176:179], v[68:71]
	v_mfma_f32_16x16x32_bf16 v[96:99], v[206:209], v[176:179], v[96:99]
	v_mfma_f32_16x16x32_bf16 v[64:67], v[198:201], v[184:187], v[64:67]
	v_mfma_f32_16x16x32_bf16 v[88:91], v[206:209], v[184:187], v[88:91]
	v_mfma_f32_16x16x32_bf16 v[76:79], v[202:205], v[164:167], v[76:79]
	v_mfma_f32_16x16x32_bf16 v[100:103], v[210:213], v[164:167], v[100:103]
	v_mfma_f32_16x16x32_bf16 v[72:75], v[202:205], v[172:175], v[72:75]
	v_mfma_f32_16x16x32_bf16 v[92:95], v[210:213], v[172:175], v[92:95]
	v_mfma_f32_16x16x32_bf16 v[68:71], v[202:205], v[180:183], v[68:71]
	v_mfma_f32_16x16x32_bf16 v[96:99], v[210:213], v[180:183], v[96:99]
	v_mfma_f32_16x16x32_bf16 v[64:67], v[202:205], v[194:197], v[64:67]
	v_mfma_f32_16x16x32_bf16 v[88:91], v[210:213], v[194:197], v[88:91]
	s_setprio 0
	s_mov_b32 m0, s39
	v_lshl_add_u64 v[218:219], s[28:29], 0, v[134:135]
	s_barrier
	ds_read_b128 v[160:163], v190 offset:16384
	ds_read_b128 v[164:167], v190 offset:17408
	ds_read_b128 v[168:171], v190 offset:18432
	ds_read_b128 v[172:175], v190 offset:19456
	ds_read_b128 v[176:179], v190 offset:20480
	ds_read_b128 v[180:183], v190 offset:21504
	ds_read_b128 v[184:187], v190 offset:22528
	ds_read_b128 v[194:197], v190 offset:23552
	global_load_lds_dwordx4 v[218:219], off
	v_lshl_add_u64 v[220:221], s[28:29], 0, v[130:131]
	s_mov_b32 m0, s40
	s_nop 0
	global_load_lds_dwordx4 v[220:221], off
	s_barrier
	s_waitcnt lgkmcnt(0)
	s_setprio 1
	s_waitcnt lgkmcnt(0)
	v_mfma_f32_16x16x32_bf16 v[60:63], v[144:147], v[160:163], v[60:63]
	v_mfma_f32_16x16x32_bf16 v[52:55], v[152:155], v[160:163], v[52:55]
	v_mfma_f32_16x16x32_bf16 v[16:19], v[144:147], v[168:171], v[16:19]
	v_mfma_f32_16x16x32_bf16 v[40:43], v[152:155], v[168:171], v[40:43]
	v_mfma_f32_16x16x32_bf16 v[20:23], v[144:147], v[176:179], v[20:23]
	v_mfma_f32_16x16x32_bf16 v[44:47], v[152:155], v[176:179], v[44:47]
	v_mfma_f32_16x16x32_bf16 v[56:59], v[144:147], v[184:187], v[56:59]
	v_mfma_f32_16x16x32_bf16 v[48:51], v[152:155], v[184:187], v[48:51]
	v_mfma_f32_16x16x32_bf16 v[60:63], v[148:151], v[164:167], v[60:63]
	v_mfma_f32_16x16x32_bf16 v[52:55], v[156:159], v[164:167], v[52:55]
	v_mfma_f32_16x16x32_bf16 v[16:19], v[148:151], v[172:175], v[16:19]
	v_mfma_f32_16x16x32_bf16 v[40:43], v[156:159], v[172:175], v[40:43]
	v_mfma_f32_16x16x32_bf16 v[20:23], v[148:151], v[180:183], v[20:23]
	v_mfma_f32_16x16x32_bf16 v[44:47], v[156:159], v[180:183], v[44:47]
	v_mfma_f32_16x16x32_bf16 v[56:59], v[148:151], v[194:197], v[56:59]
	v_mfma_f32_16x16x32_bf16 v[48:51], v[156:159], v[194:197], v[48:51]
	s_setprio 0
	s_barrier
; #define PG8_STAGE(bufoff, gbase, voff) do { _Pragma("unroll") for (int _i = 0; _i < 2; ++_i) \
;         __builtin_amdgcn_global_load_lds((const unsigned*)((const char*)(gbase) + (voff)[_i]), (LAS unsigned*)(lds + (bufoff) + ldsw + _i * 8192), 16, 0, 0); } while (0)
; #define PG8_LDA(dst, b, h) do { _Pragma("unroll") for (int m = 0; m < 4; ++m) _Pragma("unroll") for (int k = 0; k < 2; ++k) dst[m][k] = *(const LAS bf16x8*)(lds + PG8_SA(b, h) + aoff + m * 2048 + k * 1024); } while (0)
; #define PG8_LDB(dst, b, h) do { _Pragma("unroll") for (int n = 0; n < 2; ++n) _Pragma("unroll") for (int k = 0; k < 2; ++k) dst[n][k] = *(const LAS bf16x8*)(lds + PG8_SB(b, h) + boff + n * 2048 + k * 1024); } while (0)
; #define PG8_MMA(ai, bj, At, Bt) do { __builtin_amdgcn_s_setprio(1); _Pragma("unroll") for (int m = 0; m < 4; ++m) _Pragma("unroll") for (int n = 0; n < 2; ++n) _Pragma("unroll") for (int k = 0; k < 2; ++k) \
;         acc[ai][bj][m][n] = __builtin_amdgcn_mfma_f32_16x16x32_bf16(Bt[n][k], At[m][k], acc[ai][bj][m][n], 0, 0, 0); __builtin_amdgcn_s_setprio(0); } while (0)
; #define PG8_WAIT_V(n) asm volatile("s_waitcnt vmcnt(" #n ")" ::: "memory")
; #define PG8_WAIT_L(n) asm volatile("s_waitcnt lgkmcnt(" #n ")" ::: "memory")
; #define PG8_BAR __builtin_amdgcn_s_barrier()
; #define PG8_SCHED __builtin_amdgcn_sched_barrier(0)
; template <class Epi>
; __device__ __forceinline__ void gemm_phase(LAS unsigned char* lds, const Gemm g, const StaticOrder& S, const Epi& E, int wave) {
;     ...
;             PG8_WAIT_V(6); PG8_BAR; PG8_MMA(1, 1, At, B1); PG8_BAR;
;             PG8_LDB(B0, 1, 0); PG8_SCHED; PG8_LDA(At, 1, 0); PG8_STAGE(PG8_SA(0, 1), a2 + hstep, voffA);
;             PG8_WAIT_L(8); PG8_BAR; PG8_WAIT_L(0); PG8_MMA(0, 0, At, B0); PG8_BAR; PG8_SCHED;
;             PG8_LDB(B1, 1, 1); PG8_STAGE(PG8_SB(1, 0), b3, voffB);
;             PG8_BAR; PG8_WAIT_L(0); PG8_MMA(0, 1, At, B1); PG8_BAR;
;             PG8_LDA(At, 1, 1); PG8_STAGE(PG8_SA(1, 0), a3, voffA);
;             PG8_BAR; PG8_WAIT_L(0); PG8_MMA(1, 0, At, B0); PG8_BAR; PG8_SCHED;
	s_add_u32 s56, s6, 0x40000
	s_addc_u32 s57, s7, 0
	s_add_i32 s58, s51, s36
	v_lshl_add_u64 v[144:145], s[56:57], 0, v[132:133]
	s_mov_b32 m0, s58
	s_nop 0
	global_load_lds_dwordx4 v[144:145], off
	v_lshl_add_u64 v[144:145], s[56:57], 0, v[128:129]
	s_add_i32 m0, s58, 0x2000
	s_nop 0
	global_load_lds_dwordx4 v[144:145], off
	s_waitcnt vmcnt(6)
	s_barrier
	s_setprio 1
	v_mfma_f32_16x16x32_bf16 v[12:15], v[198:201], v[160:163], v[12:15]
	v_mfma_f32_16x16x32_bf16 v[36:39], v[206:209], v[160:163], v[36:39]
	v_mfma_f32_16x16x32_bf16 v[8:11], v[198:201], v[168:171], v[8:11]
	v_mfma_f32_16x16x32_bf16 v[28:31], v[206:209], v[168:171], v[28:31]
	v_mfma_f32_16x16x32_bf16 v[4:7], v[198:201], v[176:179], v[4:7]
	v_mfma_f32_16x16x32_bf16 v[32:35], v[206:209], v[176:179], v[32:35]
	v_mfma_f32_16x16x32_bf16 v[0:3], v[198:201], v[184:187], v[0:3]
	v_mfma_f32_16x16x32_bf16 v[24:27], v[206:209], v[184:187], v[24:27]
	v_mfma_f32_16x16x32_bf16 v[12:15], v[202:205], v[164:167], v[12:15]
	v_mfma_f32_16x16x32_bf16 v[36:39], v[210:213], v[164:167], v[36:39]
	v_mfma_f32_16x16x32_bf16 v[8:11], v[202:205], v[172:175], v[8:11]
	v_mfma_f32_16x16x32_bf16 v[28:31], v[210:213], v[172:175], v[28:31]
	v_mfma_f32_16x16x32_bf16 v[4:7], v[202:205], v[180:183], v[4:7]
	v_mfma_f32_16x16x32_bf16 v[32:35], v[210:213], v[180:183], v[32:35]
	v_mfma_f32_16x16x32_bf16 v[0:3], v[202:205], v[194:197], v[0:3]
	v_mfma_f32_16x16x32_bf16 v[24:27], v[210:213], v[194:197], v[24:27]
	s_setprio 0
	s_add_i32 s56, 0, 0x18000
	v_add_u32_e32 v156, s56, v188
	s_barrier
	ds_read_b128 v[144:147], v156
	ds_read_b128 v[148:151], v156 offset:1024
	ds_read_b128 v[152:155], v156 offset:2048
	ds_read_b128 v[156:159], v156 offset:3072
	s_add_u32 s28, s28, 0x40000
	s_addc_u32 s29, s29, 0
	s_mov_b32 m0, s41
	v_lshl_add_u64 v[198:199], s[28:29], 0, v[134:135]
	ds_read_b128 v[160:163], v190 offset:32768
	ds_read_b128 v[164:167], v190 offset:33792
	ds_read_b128 v[168:171], v190 offset:34816
	ds_read_b128 v[172:175], v190 offset:35840
	ds_read_b128 v[176:179], v190 offset:36864
	ds_read_b128 v[180:183], v190 offset:37888
	ds_read_b128 v[184:187], v190 offset:38912
	ds_read_b128 v[194:197], v190 offset:39936
	global_load_lds_dwordx4 v[198:199], off
	v_lshl_add_u64 v[198:199], s[28:29], 0, v[130:131]
	s_mov_b32 m0, s42
	s_nop 0
	global_load_lds_dwordx4 v[198:199], off
	s_waitcnt lgkmcnt(8)
	s_barrier
	s_waitcnt lgkmcnt(0)
	s_setprio 1
	s_waitcnt lgkmcnt(0)
	v_mfma_f32_16x16x32_bf16 v[124:127], v[144:147], v[160:163], v[124:127]
	v_mfma_f32_16x16x32_bf16 v[116:119], v[152:155], v[160:163], v[116:119]
	v_mfma_f32_16x16x32_bf16 v[80:83], v[144:147], v[168:171], v[80:83]
	v_mfma_f32_16x16x32_bf16 v[104:107], v[152:155], v[168:171], v[104:107]
	v_mfma_f32_16x16x32_bf16 v[84:87], v[144:147], v[176:179], v[84:87]
	v_mfma_f32_16x16x32_bf16 v[108:111], v[152:155], v[176:179], v[108:111]
	v_mfma_f32_16x16x32_bf16 v[120:123], v[144:147], v[184:187], v[120:123]
	v_mfma_f32_16x16x32_bf16 v[112:115], v[152:155], v[184:187], v[112:115]
	v_mfma_f32_16x16x32_bf16 v[124:127], v[148:151], v[164:167], v[124:127]
	v_mfma_f32_16x16x32_bf16 v[116:119], v[156:159], v[164:167], v[116:119]
	v_mfma_f32_16x16x32_bf16 v[80:83], v[148:151], v[172:175], v[80:83]
	v_mfma_f32_16x16x32_bf16 v[104:107], v[156:159], v[172:175], v[104:107]
	v_mfma_f32_16x16x32_bf16 v[84:87], v[148:151], v[180:183], v[84:87]
	v_mfma_f32_16x16x32_bf16 v[108:111], v[156:159], v[180:183], v[108:111]
	v_mfma_f32_16x16x32_bf16 v[120:123], v[148:151], v[194:197], v[120:123]
	v_mfma_f32_16x16x32_bf16 v[112:115], v[156:159], v[194:197], v[112:115]
	s_setprio 0
	s_barrier
	s_add_i32 s28, 0, 0x1c000
	s_add_i32 s29, s56, s36
	v_add_u32_e32 v193, s28, v188
	v_lshl_add_u64 v[214:215], v[214:215], 0, s[16:17]
	s_mov_b32 m0, s29
	ds_read_b128 v[198:201], v193
	ds_read_b128 v[202:205], v193 offset:1024
	ds_read_b128 v[206:209], v193 offset:2048
	ds_read_b128 v[210:213], v193 offset:3072
	global_load_lds_dwordx4 v[214:215], off
	v_lshl_add_u64 v[214:215], v[216:217], 0, s[16:17]
	s_add_i32 m0, s29, 0x2000
	s_nop 0
	global_load_lds_dwordx4 v[214:215], off
	s_barrier
	s_waitcnt lgkmcnt(0)
	s_setprio 1
	s_waitcnt lgkmcnt(0)
	v_mfma_f32_16x16x32_bf16 v[76:79], v[198:201], v[160:163], v[76:79]
	v_mfma_f32_16x16x32_bf16 v[100:103], v[206:209], v[160:163], v[100:103]
	v_mfma_f32_16x16x32_bf16 v[72:75], v[198:201], v[168:171], v[72:75]
	v_mfma_f32_16x16x32_bf16 v[92:95], v[206:209], v[168:171], v[92:95]
	v_mfma_f32_16x16x32_bf16 v[68:71], v[198:201], v[176:179], v[68:71]
	v_mfma_f32_16x16x32_bf16 v[96:99], v[206:209], v[176:179], v[96:99]
	v_mfma_f32_16x16x32_bf16 v[64:67], v[198:201], v[184:187], v[64:67]
	v_mfma_f32_16x16x32_bf16 v[88:91], v[206:209], v[184:187], v[88:91]
	v_mfma_f32_16x16x32_bf16 v[76:79], v[202:205], v[164:167], v[76:79]
	v_mfma_f32_16x16x32_bf16 v[100:103], v[210:213], v[164:167], v[100:103]
	v_mfma_f32_16x16x32_bf16 v[72:75], v[202:205], v[172:175], v[72:75]
	v_mfma_f32_16x16x32_bf16 v[92:95], v[210:213], v[172:175], v[92:95]
	v_mfma_f32_16x16x32_bf16 v[68:71], v[202:205], v[180:183], v[68:71]
	v_mfma_f32_16x16x32_bf16 v[96:99], v[210:213], v[180:183], v[96:99]
	v_mfma_f32_16x16x32_bf16 v[64:67], v[202:205], v[194:197], v[64:67]
	v_mfma_f32_16x16x32_bf16 v[88:91], v[210:213], v[194:197], v[88:91]
	s_setprio 0
	s_mov_b32 m0, s47
	v_lshl_add_u64 v[214:215], v[218:219], 0, s[16:17]
	s_barrier
; #define PG8_STAGE(bufoff, gbase, voff) do { _Pragma("unroll") for (int _i = 0; _i < 2; ++_i) \
;         __builtin_amdgcn_global_load_lds((const unsigned*)((const char*)(gbase) + (voff)[_i]), (LAS unsigned*)(lds + (bufoff) + ldsw + _i * 8192), 16, 0, 0); } while (0)
; #define PG8_MMA(ai, bj, At, Bt) do { __builtin_amdgcn_s_setprio(1); _Pragma("unroll") for (int m = 0; m < 4; ++m) _Pragma("unroll") for (int n = 0; n < 2; ++n) _Pragma("unroll") for (int k = 0; k < 2; ++k) \
;         acc[ai][bj][m][n] = __builtin_amdgcn_mfma_f32_16x16x32_bf16(Bt[n][k], At[m][k], acc[ai][bj][m][n], 0, 0, 0); __builtin_amdgcn_s_setprio(0); } while (0)
; #define PG8_WAIT_V(n) asm volatile("s_waitcnt vmcnt(" #n ")" ::: "memory")
; #define PG8_BAR __builtin_amdgcn_s_barrier()
; template <class Epi>
; __device__ __forceinline__ void gemm_phase(LAS unsigned char* lds, const Gemm g, const StaticOrder& S, const Epi& E, int wave) {
;     ...
;             PG8_STAGE(PG8_SB(1, 1), b3 + hstep, voffB);
;             PG8_WAIT_V(6); PG8_BAR; PG8_MMA(1, 1, At, B1); PG8_BAR;
;     __device__ __forceinline__ void operator()(f32x4 (&acc)[2][2][4][2], const pg8::Unit& u, int wr, int wc, int, int) const {
;         int ln_; asm volatile("v_mbcnt_lo_u32_b32 %0, -1, 0\n\tv_mbcnt_hi_u32_b32 %0, -1, %0" : "=v"(ln_)); const int fr = ln_ & 15, fq = ln_ >> 4;
;         const int lprev4 = ((ln_ & 48) | ((fr + 15) & 15)) << 2, lnext4 = ((ln_ & 48) | ((fr + 1) & 15)) << 2;
;         const int f0 = u.pn * 128 + wc * 32 + 8 * fq;
;         float* lwv = lw + (wr * 4 + wc) * 128;
;         { const int p0 = ln_ >> 5, col = ln_ & 31, fb = u.pn * 128 + wc * 32;
;           const float a_ = cw[p0 * DFF + fb + col]; const float b_ = (p0 == 0) ? cw[2 * DFF + fb + col] : cb[fb + col];
;           lwv[p0 * 32 + col] = a_; lwv[(p0 + 2) * 32 + col] = b_; }
;         asm volatile("s_waitcnt lgkmcnt(0)" ::: "memory");
	ds_read_b128 v[160:163], v190 offset:49152
	ds_read_b128 v[164:167], v190 offset:50176
	ds_read_b128 v[168:171], v190 offset:51200
	ds_read_b128 v[172:175], v190 offset:52224
	ds_read_b128 v[176:179], v190 offset:53248
	ds_read_b128 v[180:183], v190 offset:54272
	ds_read_b128 v[184:187], v190 offset:55296
	ds_read_b128 v[194:197], v190 offset:56320
	global_load_lds_dwordx4 v[214:215], off
	v_lshl_add_u64 v[214:215], v[220:221], 0, s[16:17]
	s_mov_b32 m0, s48
	s_nop 0
	global_load_lds_dwordx4 v[214:215], off
	s_barrier
	s_waitcnt lgkmcnt(0)
	s_setprio 1
	s_waitcnt lgkmcnt(0)
	v_mfma_f32_16x16x32_bf16 v[60:63], v[144:147], v[160:163], v[60:63]
	v_mfma_f32_16x16x32_bf16 v[52:55], v[152:155], v[160:163], v[52:55]
	v_mfma_f32_16x16x32_bf16 v[16:19], v[144:147], v[168:171], v[16:19]
	v_mfma_f32_16x16x32_bf16 v[40:43], v[152:155], v[168:171], v[40:43]
	v_mfma_f32_16x16x32_bf16 v[20:23], v[144:147], v[176:179], v[20:23]
	v_mfma_f32_16x16x32_bf16 v[44:47], v[152:155], v[176:179], v[44:47]
	v_mfma_f32_16x16x32_bf16 v[56:59], v[144:147], v[184:187], v[56:59]
	v_mfma_f32_16x16x32_bf16 v[48:51], v[152:155], v[184:187], v[48:51]
	v_mfma_f32_16x16x32_bf16 v[60:63], v[148:151], v[164:167], v[60:63]
	v_mfma_f32_16x16x32_bf16 v[52:55], v[156:159], v[164:167], v[52:55]
	v_mfma_f32_16x16x32_bf16 v[16:19], v[148:151], v[172:175], v[16:19]
	v_mfma_f32_16x16x32_bf16 v[40:43], v[156:159], v[172:175], v[40:43]
	v_mfma_f32_16x16x32_bf16 v[20:23], v[148:151], v[180:183], v[20:23]
	v_mfma_f32_16x16x32_bf16 v[44:47], v[156:159], v[180:183], v[44:47]
	v_mfma_f32_16x16x32_bf16 v[56:59], v[148:151], v[194:197], v[56:59]
	v_mfma_f32_16x16x32_bf16 v[48:51], v[156:159], v[194:197], v[48:51]
	s_setprio 0
	s_barrier
	s_add_u32 s6, s6, 0x40080
	s_addc_u32 s7, s7, 0
	s_add_i32 s28, s28, s36
	v_lshl_add_u64 v[144:145], s[6:7], 0, v[132:133]
	s_mov_b32 m0, s28
	s_nop 0
	global_load_lds_dwordx4 v[144:145], off
	v_lshl_add_u64 v[144:145], s[6:7], 0, v[128:129]
	s_add_i32 m0, s28, 0x2000
	s_nop 0
	global_load_lds_dwordx4 v[144:145], off
	s_waitcnt vmcnt(6)
	s_barrier
	s_setprio 1
	v_mfma_f32_16x16x32_bf16 v[12:15], v[198:201], v[160:163], v[12:15]
	v_mfma_f32_16x16x32_bf16 v[36:39], v[206:209], v[160:163], v[36:39]
	v_mfma_f32_16x16x32_bf16 v[8:11], v[198:201], v[168:171], v[8:11]
	v_mfma_f32_16x16x32_bf16 v[28:31], v[206:209], v[168:171], v[28:31]
	v_mfma_f32_16x16x32_bf16 v[4:7], v[198:201], v[176:179], v[4:7]
	v_mfma_f32_16x16x32_bf16 v[32:35], v[206:209], v[176:179], v[32:35]
	v_mfma_f32_16x16x32_bf16 v[0:3], v[198:201], v[184:187], v[0:3]
	v_mfma_f32_16x16x32_bf16 v[24:27], v[206:209], v[184:187], v[24:27]
	v_mfma_f32_16x16x32_bf16 v[12:15], v[202:205], v[164:167], v[12:15]
	v_mfma_f32_16x16x32_bf16 v[36:39], v[210:213], v[164:167], v[36:39]
	v_mfma_f32_16x16x32_bf16 v[8:11], v[202:205], v[172:175], v[8:11]
	v_mfma_f32_16x16x32_bf16 v[28:31], v[210:213], v[172:175], v[28:31]
	v_mfma_f32_16x16x32_bf16 v[4:7], v[202:205], v[180:183], v[4:7]
	v_mfma_f32_16x16x32_bf16 v[32:35], v[210:213], v[180:183], v[32:35]
	v_mfma_f32_16x16x32_bf16 v[0:3], v[202:205], v[194:197], v[0:3]
	v_mfma_f32_16x16x32_bf16 v[24:27], v[210:213], v[194:197], v[24:27]
	s_setprio 0
	s_add_i32 s55, s55, 2
	s_add_u32 s4, s4, 0x100
	s_addc_u32 s5, s5, 0
	s_add_u32 s31, s31, 0x100
	s_addc_u32 s54, s54, 0
	s_cmp_gt_u32 s55, 13
	s_barrier
	s_cbranch_scc0 .LBB0_810
	v_mbcnt_lo_u32_b32 v146, -1, 0
	v_mbcnt_hi_u32_b32 v146, -1, v146
	s_lshl_b32 s3, s3, 7
	v_lshrrev_b32_e32 v144, 5, v146
	s_or_b32 s3, s3, s46
	v_mul_lo_u32 v144, v144, s52
	v_and_b32_e32 v147, 31, v146
	v_add_u32_e32 v144, s3, v144
	v_or_b32_e32 v144, v144, v147
	v_readlane_b32 s56, v253, 0
	v_ashrrev_i32_e32 v145, 31, v144
	v_readlane_b32 s57, v253, 1
	s_add_i32 s4, s3, 0x1600
	v_readlane_b32 s59, v253, 3
	v_lshl_add_u64 v[144:145], v[144:145], 2, s[56:57]
	v_or_b32_e32 v144, s3, v147
	v_add_u32_e32 v145, s4, v146
	v_cmp_gt_u32_e32 vcc, 32, v146
	v_readlane_b32 s58, v253, 2
	v_mov_b32_e32 v148, s57
	v_cndmask_b32_e32 v144, v144, v145, vcc
	v_mov_b32_e32 v145, s59
	v_cndmask_b32_e32 v149, v145, v148, vcc
	v_mov_b32_e32 v145, s58
	v_mov_b32_e32 v148, s56
	v_cndmask_b32_e32 v148, v145, v148, vcc
	v_ashrrev_i32_e32 v145, 31, v144
	v_lshl_add_u64 v[144:145], v[144:145], 2, v[148:149]
	v_and_b32_e32 v148, 0x3fffffe0, v146
	v_lshl_add_u32 v145, v146, 2, s49
	v_lshlrev_b32_e32 v148, 2, v148
	v_lshlrev_b32_e32 v147, 2, v147
	v_add3_u32 v147, s49, v148, v147
	v_and_b32_e32 v193, 15, v146
	v_cmp_eq_u32_e64 s[4:5], 0, v193
	v_cmp_eq_u32_e32 vcc, 15, v193
	v_cmp_gt_i32_e64 s[6:7], 15, v193
	s_mov_b64 s[28:29], -1
	v_readlane_b32 s60, v253, 4
	v_readlane_b32 s61, v253, 5
	v_readlane_b32 s62, v253, 6
	v_readlane_b32 s63, v253, 7
	s_waitcnt vmcnt(14)
	ds_write_b32 v145, v252
	ds_write_b32 v147, v255 offset:256
	s_waitcnt lgkmcnt(0)
	s_and_saveexec_b64 s[30:31], s[6:7]
	v_cmp_eq_u32_e64 s[6:7], 0, v193
	s_orn2_b64 s[28:29], s[6:7], exec
	s_or_b64 exec, exec, s[30:31]
	v_ashrrev_i32_e32 v176, 1, v146
	v_and_b32_e32 v147, -8, v176
	v_add_u32_e32 v144, s3, v147
	s_lshl_b32 s3, s26, 8
	s_add_i32 s3, s3, s45
	v_cndmask_b32_e64 v197, 0, 1, vcc
	s_ashr_i32 s6, s3, 5
	v_ashrrev_i32_e32 v145, 31, v144
	v_or_b32_e32 v148, s6, v197
	v_mad_i64_i32 v[170:171], s[6:7], v148, s52, v[144:145]
	s_and_saveexec_b64 s[6:7], s[28:29]
	s_cbranch_execz .LBB0_815
	v_cndmask_b32_e64 v151, v67, v79, s[4:5]
	v_cndmask_b32_e64 v150, v66, v78, s[4:5]
	v_cndmask_b32_e64 v149, v65, v77, s[4:5]
	v_cndmask_b32_e64 v148, v64, v76, s[4:5]
	v_lshl_add_u64 v[152:153], v[170:171], 2, s[12:13]
	global_store_dwordx4 v[152:153], v[148:151], off

; __global__ void __launch_bounds__(NTHR, 2) fwd_kernel(Params p) {
	.amdhsa_kernel _Z10fwd_kernel6Params
		.amdhsa_group_segment_fixed_size 0
		.amdhsa_private_segment_fixed_size 0
		.amdhsa_kernarg_size 504
		.amdhsa_user_sgpr_count 2
		.amdhsa_user_sgpr_dispatch_ptr 0
		.amdhsa_user_sgpr_queue_ptr 0
		.amdhsa_user_sgpr_kernarg_segment_ptr 1
		.amdhsa_user_sgpr_dispatch_id 0
		.amdhsa_user_sgpr_kernarg_preload_length 0
		.amdhsa_user_sgpr_kernarg_preload_offset 0
		.amdhsa_user_sgpr_private_segment_size 0
		.amdhsa_uses_dynamic_stack 0
		.amdhsa_enable_private_segment 0
		.amdhsa_system_sgpr_workgroup_id_x 1
		.amdhsa_system_sgpr_workgroup_id_y 0
		.amdhsa_system_sgpr_workgroup_id_z 0
		.amdhsa_system_sgpr_workgroup_info 0
		.amdhsa_system_vgpr_workitem_id 2
		.amdhsa_next_free_vgpr 256
		.amdhsa_next_free_sgpr 102
		.amdhsa_accum_offset 256
		.amdhsa_reserve_vcc 1
		.amdhsa_float_round_mode_32 0
		.amdhsa_float_round_mode_16_64 0
		.amdhsa_float_denorm_mode_32 3
		.amdhsa_float_denorm_mode_16_64 3
		.amdhsa_dx10_clamp 1
		.amdhsa_ieee_mode 1
		.amdhsa_fp16_overflow 0
		.amdhsa_tg_split 0
		.amdhsa_exception_fp_ieee_invalid_op 0
		.amdhsa_exception_fp_denorm_src 0
		.amdhsa_exception_fp_ieee_div_zero 0
		.amdhsa_exception_fp_ieee_overflow 0
		.amdhsa_exception_fp_ieee_underflow 0
		.amdhsa_exception_fp_ieee_inexact 0
		.amdhsa_exception_int_div_zero 0
	.end_amdhsa_kernel

; __global__ void __launch_bounds__(NTHR, 2) fwd_kernel(Params p) {
amdhsa.kernels:
  - .agpr_count:     0
    .args:
      - .offset:         0
        .size:           248
        .value_kind:     by_value
      - .offset:         248
        .size:           4
        .value_kind:     hidden_block_count_x
      - .offset:         252
        .size:           4
        .value_kind:     hidden_block_count_y
      - .offset:         256
        .size:           4
        .value_kind:     hidden_block_count_z
      - .offset:         260
        .size:           2
        .value_kind:     hidden_group_size_x
      - .offset:         262
        .size:           2
        .value_kind:     hidden_group_size_y
      - .offset:         264
        .size:           2
        .value_kind:     hidden_group_size_z
      - .offset:         266
        .size:           2
        .value_kind:     hidden_remainder_x
      - .offset:         268
        .size:           2
        .value_kind:     hidden_remainder_y
      - .offset:         270
        .size:           2
        .value_kind:     hidden_remainder_z
      - .offset:         288
        .size:           8
        .value_kind:     hidden_global_offset_x
      - .offset:         296
        .size:           8
        .value_kind:     hidden_global_offset_y
      - .offset:         304
        .size:           8
        .value_kind:     hidden_global_offset_z
      - .offset:         312
        .size:           2
        .value_kind:     hidden_grid_dims
      - .offset:         336
        .size:           8
        .value_kind:     hidden_multigrid_sync_arg
      - .offset:         368
        .size:           4
        .value_kind:     hidden_dynamic_lds_size
    .group_segment_fixed_size: 0
    .kernarg_segment_align: 8
    .kernarg_segment_size: 504
    .language:       OpenCL C
    .language_version:
      - 2
      - 0
    .max_flat_workgroup_size: 512
    .name:           _Z10fwd_kernel6Params
    .private_segment_fixed_size: 0
    .sgpr_count:     108
    .sgpr_spill_count: 139
    .symbol:         _Z10fwd_kernel6Params.kd
    .uniform_work_group_size: 1
    .uses_dynamic_stack: false
    .vgpr_count:     256
    .vgpr_spill_count: 0
    .wavefront_size: 64
